# speedup vs baseline: 1.1108x; 1.0034x over previous
; #define WAIT_V(n) asm volatile("s_waitcnt vmcnt(%0)" ::"n"(n) : "memory")
;     ...
;     for (int t = 0; t < nt; ++t) {
;       const int cur = t & 1;
;       const char* sa = shm + cur * STAGE_B;
;       const char* sn = shm + (cur ^ 1) * STAGE_B;
;       const bool more = (t + 1 < nt) || (nitem < ntiles);
; #pragma unroll
;       for (int ks = 0; ks < 2; ++ks) {
; #pragma unroll
;         for (int p = 0; p < NP; ++p) {
;           const int q = ks * NP + p;
;           acc[p * 2][0] = __builtin_amdgcn_mfma_f32_16x16x32_bf16(Bq[BDBL ? ks : 0][0], Aq[q & 1][0], acc[p * 2][0], 0, 0, 0);
;           __builtin_amdgcn_sched_barrier(0);
;           if (q == 2 * NP - 1) {
;             WAIT_V(0);
;             __syncthreads();
;             if (more) {
;               if constexpr (BDBL) {
; #pragma unroll
;                 for (int n = 0; n < 4; ++n) Bq[0][n] = *(const bf16x8*)(sn + boff + (n * 2 + 0) * 1024);
;               }
; #pragma unroll
;               for (int i = 0; i < 2; ++i) Aq[0][i] = *(const bf16x8*)(sn + aoff + (i * 2 + 0) * 1024);
;             }
;           } else if (p + 1 < NP) {
; #pragma unroll
;             for (int i = 0; i < 2; ++i) Aq[(q + 1) & 1][i] = *(const bf16x8*)(sa + aoff + (((p + 1) * 2 + i) * 2 + ks) * 1024);
;           } else {
;             if constexpr (BDBL) {
; #pragma unroll
;               for (int n = 0; n < 4; ++n) Bq[1][n] = *(const bf16x8*)(sa + boff + (n * 2 + 1) * 1024);
;             }
; #pragma unroll
;             for (int i = 0; i < 2; ++i) Aq[(q + 1) & 1][i] = *(const bf16x8*)(sa + aoff + (i * 2 + 1) * 1024);
;           }
;           __builtin_amdgcn_sched_barrier(0);
; #pragma unroll
;           for (int i = 0; i < 2; ++i)
; #pragma unroll
;             for (int n = 0; n < 4; ++n)
;               if (i + n > 0)
;                 acc[p * 2 + i][n] = __builtin_amdgcn_mfma_f32_16x16x32_bf16(Bq[BDBL ? ks : 0][n], Aq[q & 1][i], acc[p * 2 + i][n], 0, 0, 0);
;           __builtin_amdgcn_sched_barrier(0);
;           if (q == GLDS_AT) {
;             if (t + 1 < nt) GLDS_STAGE(cur ^ 1, t + 1, Ab, Bb);
;             else if (nitem < ntiles) GLDS_STAGE(0, 0, nAb, nBb);
;             __builtin_amdgcn_sched_barrier(0);
;           }
.LBB0_253:
	s_waitcnt lgkmcnt(0)
	s_nop 0
	v_mfma_f32_16x16x32_bf16 v[84:87], v[12:15], v[20:23], v[84:87]
	s_and_b32 s20, s58, 1
	s_mul_i32 s21, s20, 0xc000
	s_xor_b32 s20, s20, 1
	s_add_i32 s58, s58, 1
	s_mul_i32 s20, s20, 0xc000
	v_add_u32_e32 v112, s21, v135
	v_add_u32_e32 v120, s21, v134
	v_add_u32_e32 v121, s20, v135
	v_add_u32_e32 v122, s20, v134
	ds_read_b128 v[92:95], v120 offset:4096
	ds_read_b128 v[96:99], v120 offset:6144
	v_mfma_f32_16x16x32_bf16 v[80:83], v[8:11], v[20:23], v[80:83]
	s_add_i32 s20, s20, s95
	v_lshl_add_u64 v[116:117], v[90:91], 0, s[0:1]
	v_lshl_add_u64 v[118:119], v[116:117], 0, s[38:39]
	s_mov_b32 m0, s20
	v_mfma_f32_16x16x32_bf16 v[76:79], v[4:7], v[20:23], v[76:79]
	v_lshl_add_u64 v[116:117], v[116:117], 0, s[72:73]
	global_load_lds_dwordx4 v[118:119], off
	s_add_i32 m0, s20, 0x2000
	s_add_i32 s21, s20, 0x4000
	v_mfma_f32_16x16x32_bf16 v[20:23], v[0:3], v[20:23], v[72:75]
	global_load_lds_dwordx4 v[116:117], off
	v_lshl_add_u64 v[116:117], v[88:89], 0, s[0:1]
	v_lshl_add_u64 v[118:119], v[116:117], 0, s[38:39]
	s_mov_b32 m0, s21
	v_mfma_f32_16x16x32_bf16 v[68:71], v[12:15], v[16:19], v[68:71]
	global_load_lds_dwordx4 v[118:119], off
	v_lshl_add_u64 v[118:119], v[116:117], 0, s[72:73]
	s_add_i32 m0, s20, 0x6000
	v_mfma_f32_16x16x32_bf16 v[64:67], v[8:11], v[16:19], v[64:67]
	global_load_lds_dwordx4 v[118:119], off
	v_lshl_add_u64 v[118:119], v[116:117], 0, s[54:55]
	s_add_i32 m0, s20, 0x8000
	v_lshl_add_u64 v[116:117], v[116:117], 0, s[80:81]
	v_mfma_f32_16x16x32_bf16 v[60:63], v[4:7], v[16:19], v[60:63]
	global_load_lds_dwordx4 v[118:119], off
	s_add_i32 m0, s20, 0xa000
	v_mfma_f32_16x16x32_bf16 v[16:19], v[0:3], v[16:19], v[56:59]
	global_load_lds_dwordx4 v[116:117], off
	s_waitcnt lgkmcnt(1)
	v_mfma_f32_16x16x32_bf16 v[52:55], v[12:15], v[92:95], v[52:55]
	ds_read_b128 v[100:103], v112 offset:17408
	ds_read_b128 v[104:107], v112 offset:19456
	ds_read_b128 v[108:111], v112 offset:21504
	ds_read_b128 v[112:115], v112 offset:23552
	ds_read_b128 v[56:59], v120 offset:1024
	ds_read_b128 v[116:119], v120 offset:3072
	v_mfma_f32_16x16x32_bf16 v[48:51], v[8:11], v[92:95], v[48:51]
	v_mfma_f32_16x16x32_bf16 v[44:47], v[4:7], v[92:95], v[44:47]
	v_mfma_f32_16x16x32_bf16 v[40:43], v[0:3], v[92:95], v[40:43]
	s_waitcnt lgkmcnt(6)
	v_mfma_f32_16x16x32_bf16 v[36:39], v[12:15], v[96:99], v[36:39]
	v_mfma_f32_16x16x32_bf16 v[32:35], v[8:11], v[96:99], v[32:35]
	v_mfma_f32_16x16x32_bf16 v[28:31], v[4:7], v[96:99], v[28:31]
	v_mfma_f32_16x16x32_bf16 v[24:27], v[0:3], v[96:99], v[24:27]
	s_waitcnt lgkmcnt(0)
	v_mfma_f32_16x16x32_bf16 v[84:87], v[100:103], v[56:59], v[84:87]
	ds_read_b128 v[92:95], v120 offset:5120
	ds_read_b128 v[96:99], v120 offset:7168
	v_mfma_f32_16x16x32_bf16 v[80:83], v[104:107], v[56:59], v[80:83]
	v_mfma_f32_16x16x32_bf16 v[76:79], v[108:111], v[56:59], v[76:79]
	v_mfma_f32_16x16x32_bf16 v[72:75], v[112:115], v[56:59], v[20:23]
	v_mfma_f32_16x16x32_bf16 v[68:71], v[100:103], v[116:119], v[68:71]
	v_mfma_f32_16x16x32_bf16 v[64:67], v[104:107], v[116:119], v[64:67]
	v_mfma_f32_16x16x32_bf16 v[60:63], v[108:111], v[116:119], v[60:63]
	v_mfma_f32_16x16x32_bf16 v[56:59], v[112:115], v[116:119], v[16:19]
	s_waitcnt lgkmcnt(1)
	v_mfma_f32_16x16x32_bf16 v[52:55], v[100:103], v[92:95], v[52:55]
	s_waitcnt vmcnt(0)
	s_waitcnt lgkmcnt(0)
	s_barrier
	ds_read_b128 v[12:15], v121 offset:16384
	ds_read_b128 v[8:11], v121 offset:18432
	ds_read_b128 v[4:7], v121 offset:20480
	ds_read_b128 v[0:3], v121 offset:22528
	ds_read_b128 v[20:23], v122
	ds_read_b128 v[16:19], v122 offset:2048
	v_mfma_f32_16x16x32_bf16 v[48:51], v[104:107], v[92:95], v[48:51]
	v_mfma_f32_16x16x32_bf16 v[44:47], v[108:111], v[92:95], v[44:47]
	v_mfma_f32_16x16x32_bf16 v[40:43], v[112:115], v[92:95], v[40:43]
	v_mfma_f32_16x16x32_bf16 v[36:39], v[100:103], v[96:99], v[36:39]
	v_mfma_f32_16x16x32_bf16 v[32:35], v[104:107], v[96:99], v[32:35]
	v_mfma_f32_16x16x32_bf16 v[28:31], v[108:111], v[96:99], v[28:31]
	v_mfma_f32_16x16x32_bf16 v[24:27], v[112:115], v[96:99], v[24:27]
	s_add_u32 s0, s0, 0x80
	s_addc_u32 s1, s1, 0
	s_cmp_eq_u32 s59, s0
	s_cbranch_scc0 .LBB0_253
	s_waitcnt lgkmcnt(1)
	v_mfma_f32_16x16x32_bf16 v[84:87], v[12:15], v[20:23], v[84:87]
	s_and_b32 s20, s58, 1
	s_mul_i32 s0, s20, 0xc000
	v_add_u32_e32 v96, s0, v135
	v_add_u32_e32 v128, s0, v134
	ds_read_b128 v[100:103], v128 offset:4096
	ds_read_b128 v[138:141], v128 offset:6144
	v_mfma_f32_16x16x32_bf16 v[80:83], v[8:11], v[20:23], v[80:83]
	v_mfma_f32_16x16x32_bf16 v[76:79], v[4:7], v[20:23], v[76:79]
	v_mfma_f32_16x16x32_bf16 v[108:111], v[0:3], v[20:23], v[72:75]
	s_waitcnt lgkmcnt(2)
	v_mfma_f32_16x16x32_bf16 v[112:115], v[12:15], v[16:19], v[68:71]
	v_mfma_f32_16x16x32_bf16 v[64:67], v[8:11], v[16:19], v[64:67]
	v_mfma_f32_16x16x32_bf16 v[116:119], v[4:7], v[16:19], v[60:63]
	v_mfma_f32_16x16x32_bf16 v[120:123], v[0:3], v[16:19], v[56:59]
	s_waitcnt lgkmcnt(1)
	v_mfma_f32_16x16x32_bf16 v[124:127], v[12:15], v[100:103], v[52:55]
	s_nop 0
	ds_read_b128 v[56:59], v96 offset:17408
	ds_read_b128 v[88:91], v96 offset:19456
	ds_read_b128 v[92:95], v96 offset:21504
	ds_read_b128 v[96:99], v96 offset:23552
	ds_read_b128 v[20:23], v128 offset:1024
	ds_read_b128 v[16:19], v128 offset:3072
	v_mfma_f32_16x16x32_bf16 v[60:63], v[8:11], v[100:103], v[48:51]
	v_mfma_f32_16x16x32_bf16 v[44:47], v[4:7], v[100:103], v[44:47]
	v_mfma_f32_16x16x32_bf16 v[40:43], v[0:3], v[100:103], v[40:43]
	s_waitcnt lgkmcnt(6)
	v_mfma_f32_16x16x32_bf16 v[72:75], v[12:15], v[138:141], v[36:39]
	v_mfma_f32_16x16x32_bf16 v[100:103], v[8:11], v[138:141], v[32:35]
	v_mfma_f32_16x16x32_bf16 v[104:107], v[4:7], v[138:141], v[28:31]
	v_mfma_f32_16x16x32_bf16 v[24:27], v[0:3], v[138:141], v[24:27]
	s_nop 1
	v_cndmask_b32_e64 v28, 0, 1, s[6:7]
	v_cmp_ne_u32_e64 s[0:1], 1, v28
	s_andn2_b64 vcc, exec, s[6:7]
	s_cbranch_vccnz .LBB0_256
	s_mov_b32 m0, s95
	v_lshl_add_u64 v[28:29], s[14:15], 0, v[224:225]
	s_mov_b64 s[6:7], 0x58000
	v_lshl_add_u64 v[32:33], v[28:29], 0, s[6:7]
	global_load_lds_dwordx4 v[28:29], off
	s_add_i32 m0, s95, 0x2000
	v_lshl_add_u64 v[30:31], s[18:19], 0, v[224:225]
	global_load_lds_dwordx4 v[32:33], off
	s_add_i32 m0, s95, 0x4000
	v_lshl_add_u64 v[34:35], v[30:31], 0, s[6:7]
	s_mov_b64 s[6:7], 0xb0000
	global_load_lds_dwordx4 v[30:31], off
	s_add_i32 m0, s95, 0x6000
	v_lshl_add_u64 v[36:37], v[30:31], 0, s[6:7]
	s_mov_b64 s[6:7], 0x108000
	global_load_lds_dwordx4 v[34:35], off
	s_add_i32 m0, s95, 0x8000
	v_lshl_add_u64 v[38:39], v[30:31], 0, s[6:7]
	global_load_lds_dwordx4 v[36:37], off
	s_add_i32 m0, s95, 0xa000
	s_nop 0
	global_load_lds_dwordx4 v[38:39], off
